# attention main loop at its VALU floor: all42 + half-row rescale decision (cross-half exchange only in the rescale blocks) + SGPR-base DMA sources and preheader rescale address (all45 and all44 combine
# speedup vs baseline: 1.0012x; 1.0012x over previous
.LBB0_1547:
	v_add_u32_e32 v0, s8, v221
	ds_read_b64_tr_b16 v[192:193], v0 offset:24576
	ds_read_b64_tr_b16 v[194:195], v0 offset:25088
	s_waitcnt lgkmcnt(9)
	v_mfma_f32_32x32x16_bf16 v[112:127], v[188:191], v[148:151], v[48:63]
	v_add_f32_e32 v2, v80, v81
	v_add_f32_e32 v2, v82, v2
	v_add_f32_e32 v2, v83, v2
	v_add_f32_e32 v2, v84, v2
	v_add_f32_e32 v2, v85, v2
	v_cvt_pk_bf16_f32 v156, v80, v81
	v_cvt_pk_bf16_f32 v157, v82, v83
	ds_read_b64_tr_b16 v[188:189], v0 offset:28672
	ds_read_b64_tr_b16 v[190:191], v0 offset:29184
	s_waitcnt lgkmcnt(10)
	v_mfma_f32_32x32x16_bf16 v[96:111], v[184:187], v[148:151], v[48:63]
	v_add_f32_e32 v2, v86, v2
	v_add_f32_e32 v2, v87, v2
	v_add_f32_e32 v2, v88, v2
	v_add_f32_e32 v2, v89, v2
	v_cvt_pk_bf16_f32 v158, v84, v85
	v_cvt_pk_bf16_f32 v159, v86, v87
	ds_read_b64_tr_b16 v[184:185], v0 offset:25600
	ds_read_b64_tr_b16 v[186:187], v0 offset:26112
	s_waitcnt lgkmcnt(11)
	v_mfma_f32_32x32x16_bf16 v[112:127], v[180:183], v[140:143], v[112:127]
	v_add_f32_e32 v2, v90, v2
	v_add_f32_e32 v2, v91, v2
	v_add_f32_e32 v2, v92, v2
	v_add_f32_e32 v2, v93, v2
	v_cvt_pk_bf16_f32 v152, v88, v89
	v_cvt_pk_bf16_f32 v153, v90, v91
	ds_read_b64_tr_b16 v[84:85], v0 offset:29696
	ds_read_b64_tr_b16 v[86:87], v0 offset:30208
	s_waitcnt lgkmcnt(12)
	v_mfma_f32_32x32x16_bf16 v[96:111], v[176:179], v[140:143], v[96:111]
	v_add_f32_e32 v2, v94, v2
	v_add_f32_e32 v2, v95, v2
	v_add_f32_e32 v2, v64, v2
	v_add_f32_e32 v2, v65, v2
	v_cvt_pk_bf16_f32 v154, v92, v93
	v_cvt_pk_bf16_f32 v155, v94, v95
	ds_read_b64_tr_b16 v[80:81], v0 offset:26624
	ds_read_b64_tr_b16 v[82:83], v0 offset:27136
	s_waitcnt lgkmcnt(13)
	v_mfma_f32_32x32x16_bf16 v[112:127], v[172:175], v[132:135], v[112:127]
	v_add_f32_e32 v2, v66, v2
	v_add_f32_e32 v2, v67, v2
	v_add_f32_e32 v2, v68, v2
	v_add_f32_e32 v2, v69, v2
	v_cvt_pk_bf16_f32 v144, v64, v65
	v_cvt_pk_bf16_f32 v145, v66, v67
	ds_read_b64_tr_b16 v[10:11], v0 offset:30720
	ds_read_b64_tr_b16 v[12:13], v0 offset:31232
	s_waitcnt lgkmcnt(14)
	v_mfma_f32_32x32x16_bf16 v[96:111], v[168:171], v[132:135], v[96:111]
	v_add_f32_e32 v2, v70, v2
	v_add_f32_e32 v2, v71, v2
	v_add_f32_e32 v2, v72, v2
	v_add_f32_e32 v2, v73, v2
	v_cvt_pk_bf16_f32 v146, v68, v69
	v_cvt_pk_bf16_f32 v147, v70, v71
	ds_read_b64_tr_b16 v[6:7], v0 offset:27648
	ds_read_b64_tr_b16 v[8:9], v0 offset:28160
	s_waitcnt lgkmcnt(14)
	v_mfma_f32_32x32x16_bf16 v[112:127], v[164:167], v[128:131], v[112:127]
	v_add_f32_e32 v2, v74, v2
	v_add_f32_e32 v2, v75, v2
	v_add_f32_e32 v2, v76, v2
	v_add_f32_e32 v14, v77, v2
	v_cvt_pk_bf16_f32 v136, v72, v73
	v_cvt_pk_bf16_f32 v137, v74, v75
	ds_read_b64_tr_b16 v[2:3], v0 offset:31744
	ds_read_b64_tr_b16 v[4:5], v0 offset:32256
	v_mfma_f32_32x32x16_bf16 v[96:111], v[160:163], v[128:131], v[96:111]
	v_add_f32_e32 v0, v78, v14
	v_add_f32_e32 v0, v79, v0
	v_cvt_pk_bf16_f32 v138, v76, v77
	v_cvt_pk_bf16_f32 v139, v78, v79
	s_add_u32 s94, s88, s26
	s_addc_u32 s95, s89, s27
	s_add_i32 s8, s40, s46
	s_mov_b32 s9, m0
	s_mov_b32 m0, s8
	s_add_u32 s96, s90, s26
	s_addc_u32 s97, s91, s27
	global_load_lds_dwordx4 v224, s[94:95]
	s_add_i32 s8, s38, s47
	s_mov_b32 m0, s8
	s_nop 0
	global_load_lds_dwordx4 v225, s[96:97]
	s_mov_b32 m0, s9
	v_max3_f32 v14, v112, v113, v114
	v_max3_f32 v15, v115, v116, v117
	v_max3_f32 v14, v14, v118, v119
	v_max3_f32 v15, v15, v120, v121
	v_max3_f32 v14, v14, v122, v123
	v_max3_f32 v15, v15, v124, v125
	v_max3_f32 v14, v14, v126, v127
	v_max3_f32 v15, v15, v96, v97
	v_max3_f32 v14, v14, v98, v99
	v_max3_f32 v15, v15, v100, v101
	v_max3_f32 v14, v14, v102, v103
	v_max3_f32 v15, v15, v104, v105
	v_max3_f32 v14, v14, v106, v107
	v_max3_f32 v15, v15, v108, v109
	v_max3_f32 v64, v14, v110, v111
	v_add_f32_e32 v14, v223, v0
	v_max_f32_e32 v0, v64, v15
	s_mov_b64 s[8:9], 0
	v_cmp_lt_f32_e32 vcc, s53, v0
	s_cbranch_vccnz .LBB0_1555

.LBB0_1550:
	s_add_i32 s8, s38, 0x2000
	s_cmpk_lg_i32 s38, 0x4000
	s_cselect_b32 s13, s8, 0
	v_add_u32_e32 v4, s40, v221
	ds_read_b64_tr_b16 v[168:169], v4 offset:24576
	ds_read_b64_tr_b16 v[170:171], v4 offset:25088
	s_waitcnt lgkmcnt(9)
	v_mfma_f32_32x32x16_bf16 v[80:95], v[64:67], v[148:151], v[48:63]
	v_add_f32_e32 v2, v112, v113
	v_add_f32_e32 v2, v114, v2
	v_add_f32_e32 v2, v115, v2
	v_add_f32_e32 v2, v116, v2
	v_add_f32_e32 v2, v117, v2
	v_cvt_pk_bf16_f32 v156, v112, v113
	v_cvt_pk_bf16_f32 v157, v114, v115
	ds_read_b64_tr_b16 v[164:165], v4 offset:28672
	ds_read_b64_tr_b16 v[166:167], v4 offset:29184
	s_waitcnt lgkmcnt(10)
	v_mfma_f32_32x32x16_bf16 v[64:79], v[160:163], v[148:151], v[48:63]
	v_add_f32_e32 v2, v118, v2
	v_add_f32_e32 v2, v119, v2
	v_add_f32_e32 v2, v120, v2
	v_add_f32_e32 v2, v121, v2
	v_cvt_pk_bf16_f32 v158, v116, v117
	v_cvt_pk_bf16_f32 v159, v118, v119
	ds_read_b64_tr_b16 v[160:161], v4 offset:25600
	ds_read_b64_tr_b16 v[162:163], v4 offset:26112
	s_waitcnt lgkmcnt(11)
	v_mfma_f32_32x32x16_bf16 v[80:95], v[192:195], v[140:143], v[80:95]
	v_add_f32_e32 v2, v122, v2
	v_add_f32_e32 v2, v123, v2
	v_add_f32_e32 v2, v124, v2
	v_add_f32_e32 v2, v125, v2
	v_cvt_pk_bf16_f32 v152, v120, v121
	v_cvt_pk_bf16_f32 v153, v122, v123
	ds_read_b64_tr_b16 v[116:117], v4 offset:29696
	ds_read_b64_tr_b16 v[118:119], v4 offset:30208
	s_waitcnt lgkmcnt(12)
	v_mfma_f32_32x32x16_bf16 v[64:79], v[184:187], v[140:143], v[64:79]
	v_add_f32_e32 v2, v126, v2
	v_add_f32_e32 v2, v127, v2
	v_add_f32_e32 v2, v96, v2
	v_add_f32_e32 v2, v97, v2
	v_cvt_pk_bf16_f32 v154, v124, v125
	v_cvt_pk_bf16_f32 v155, v126, v127
	ds_read_b64_tr_b16 v[112:113], v4 offset:26624
	ds_read_b64_tr_b16 v[114:115], v4 offset:27136
	s_waitcnt lgkmcnt(13)
	v_mfma_f32_32x32x16_bf16 v[80:95], v[188:191], v[132:135], v[80:95]
	v_add_f32_e32 v2, v98, v2
	v_add_f32_e32 v2, v99, v2
	v_add_f32_e32 v2, v100, v2
	v_add_f32_e32 v2, v101, v2
	v_cvt_pk_bf16_f32 v144, v96, v97
	v_cvt_pk_bf16_f32 v145, v98, v99
	ds_read_b64_tr_b16 v[10:11], v4 offset:30720
	ds_read_b64_tr_b16 v[12:13], v4 offset:31232
	s_waitcnt lgkmcnt(14)
	v_mfma_f32_32x32x16_bf16 v[64:79], v[176:179], v[132:135], v[64:79]
	v_add_f32_e32 v2, v102, v2
	v_add_f32_e32 v2, v103, v2
	v_add_f32_e32 v2, v104, v2
	v_add_f32_e32 v2, v105, v2
	v_cvt_pk_bf16_f32 v146, v100, v101
	v_cvt_pk_bf16_f32 v147, v102, v103
	ds_read_b64_tr_b16 v[6:7], v4 offset:27648
	ds_read_b64_tr_b16 v[8:9], v4 offset:28160
	s_waitcnt lgkmcnt(14)
	v_mfma_f32_32x32x16_bf16 v[80:95], v[180:183], v[128:131], v[80:95]
	v_add_f32_e32 v2, v106, v2
	v_add_f32_e32 v2, v107, v2
	v_add_f32_e32 v2, v108, v2
	v_add_f32_e32 v15, v109, v2
	v_cvt_pk_bf16_f32 v136, v104, v105
	v_cvt_pk_bf16_f32 v137, v106, v107
	ds_read_b64_tr_b16 v[2:3], v4 offset:31744
	ds_read_b64_tr_b16 v[4:5], v4 offset:32256
	v_mfma_f32_32x32x16_bf16 v[64:79], v[172:175], v[128:131], v[64:79]
	v_add_f32_e32 v15, v110, v15
	v_add_f32_e32 v15, v111, v15
	v_cvt_pk_bf16_f32 v138, v108, v109
	v_cvt_pk_bf16_f32 v139, v110, v111
	v_max3_f32 v96, v80, v81, v82
	v_max3_f32 v97, v83, v84, v85
	v_max3_f32 v96, v96, v86, v87
	v_max3_f32 v97, v97, v88, v89
	v_max3_f32 v96, v96, v90, v91
	v_max3_f32 v97, v97, v92, v93
	v_max3_f32 v96, v96, v94, v95
	v_add_f32_e32 v223, v14, v15
	s_nop 0
	v_max3_f32 v97, v97, v64, v65
	v_max3_f32 v96, v96, v66, v67
	v_max3_f32 v97, v97, v68, v69
	v_max3_f32 v96, v96, v70, v71
	v_max3_f32 v97, v97, v72, v73
	v_max3_f32 v96, v96, v74, v75
	v_max3_f32 v97, v97, v76, v77
	v_max3_f32 v96, v96, v78, v79
	v_max_f32_e32 v14, v96, v97
	s_add_i32 s8, s38, s46
	s_mov_b32 s9, m0
	s_mov_b32 m0, s8
	s_nop 0
	global_load_lds_dwordx4 v224, s[88:89]
	s_mov_b32 m0, s9
	s_add_i32 s8, s13, s47
	s_mov_b32 s9, m0
	s_mov_b32 m0, s8
	s_nop 0
	global_load_lds_dwordx4 v225, s[90:91]
	s_mov_b32 m0, s9
	s_mov_b64 s[8:9], 0
	v_cmp_lt_f32_e32 vcc, s53, v14
	s_cbranch_vccnz .LBB0_1558
